# v10 plus cvt_pk groups issued right behind the previous PV MFMA (pads removed)
# speedup vs baseline: 1.0150x; 1.0029x over previous
; #define SBAR() __builtin_amdgcn_sched_barrier(0)
; template <int DQK, int MODE, bool PIPE>
; DI void attn_core(const u16* __restrict__ Qg, const u16* __restrict__ Kg, const u16* __restrict__ Vtg, int ntiles,
;                   int kr_lo, int rs, int r_q, int c_q, int cs, const float* biasL, char* lds, f32x16 (&o)[4], float& l_out, int tid) {
;     ...
;     for (int i = 0; i < 16; ++i) { p0[i] = __builtin_amdgcn_exp2f(p0[i]); p1[i] = __builtin_amdgcn_exp2f(p1[i]); ps += p0[i] + p1[i]; }
;     l += ps;
;     const char* vb = lds + (t & 1) * A_BUF + A_VOFF + r32 * 136 + h * 8;
;     {
;       bf16x8 pfc;
;       constexpr int R = PV_RING;
;       const unsigned vaddr = (unsigned)(size_t)vb;
;       s16x4 vlo[R], vhi[R];
;       SBAR();
;       vlo[0] = lds_rd64<0>(vaddr); vhi[0] = lds_rd64<16>(vaddr);
;       vlo[1] = lds_rd64<32 * 136>(vaddr); vhi[1] = lds_rd64<32 * 136 + 16>(vaddr);
;       if (R > 2) { vlo[2 % R] = lds_rd64<64 * 136>(vaddr); vhi[2 % R] = lds_rd64<64 * 136 + 16>(vaddr); }
;       if (R > 3) { vlo[3 % R] = lds_rd64<96 * 136>(vaddr); vhi[3 % R] = lds_rd64<96 * 136 + 16>(vaddr); }
;       SBAR();
;       __builtin_amdgcn_s_setprio(1);
;       PvStep<0, 16, R>::run(vaddr, vlo, vhi, p0, p1, pfc, o);
;       __builtin_amdgcn_s_setprio(0);
;     ...
;       if (t + 2 < ntiles) swriteK(t & 1);
;       if (t + 3 < ntiles) gloadK(t + 3);
;     } else {
;       if (is_active(t)) { qk(t, c0, c1); sm_pv(t, c0, c1); }
;       if (t + 1 < ntiles) swriteK((t + 1) & 1);
;       if (t + 2 < ntiles) gloadK(t + 2);
.LBB0_825:
	v_exp_f32_e32 v66, v66
	v_exp_f32_e32 v82, v82
	v_exp_f32_e32 v67, v67
	v_exp_f32_e32 v83, v83
	v_exp_f32_e32 v68, v68
	v_exp_f32_e32 v84, v84
	v_exp_f32_e32 v69, v69
	v_exp_f32_e32 v85, v85
	v_exp_f32_e32 v70, v70
	v_exp_f32_e32 v86, v86
	v_exp_f32_e32 v71, v71
	v_exp_f32_e32 v87, v87
	v_exp_f32_e32 v72, v72
	v_exp_f32_e32 v88, v88
	v_exp_f32_e32 v73, v73
	v_exp_f32_e32 v89, v89
	v_exp_f32_e32 v74, v74
	v_exp_f32_e32 v90, v90
	v_exp_f32_e32 v75, v75
	v_exp_f32_e32 v91, v91
	v_exp_f32_e32 v76, v76
	v_exp_f32_e32 v92, v92
	v_exp_f32_e32 v77, v77
	v_exp_f32_e32 v93, v93
	v_exp_f32_e32 v78, v78
	v_exp_f32_e32 v94, v94
	v_exp_f32_e32 v79, v79
	v_exp_f32_e32 v95, v95
	v_exp_f32_e32 v80, v80
	v_exp_f32_e32 v96, v96
	v_exp_f32_e32 v81, v81
	v_exp_f32_e32 v97, v97
	v_add_u32_e32 v228, s19, v226
	v_add3_u32 v248, v228, v168, s33
	ds_read_b64 v[228:229], v248 offset:0
	ds_read_b64 v[230:231], v248 offset:16
	ds_read_b64 v[232:233], v248 offset:0x1100
	ds_read_b64 v[234:235], v248 offset:0x1110
	ds_read_b64 v[236:237], v248 offset:0x2200
	ds_read_b64 v[238:239], v248 offset:0x2210
	ds_read_b64 v[240:241], v248 offset:0x3300
	ds_read_b64 v[242:243], v248 offset:0x3310
	s_setprio 1
	s_waitcnt lgkmcnt(4)
	v_cvt_pk_bf16_f32 v244, v66, v67
	v_cvt_pk_bf16_f32 v245, v68, v69
	v_cvt_pk_bf16_f32 v246, v70, v71
	v_cvt_pk_bf16_f32 v247, v72, v73
	s_nop 1
	v_mfma_f32_32x32x16_bf16 v[50:65], v[228:231], v[244:247], v[50:65]
	ds_read_b64 v[228:229], v248 offset:32
	ds_read_b64 v[230:231], v248 offset:48
	v_mfma_f32_32x32x16_bf16 v[34:49], v[232:235], v[244:247], v[34:49]
	ds_read_b64 v[232:233], v248 offset:0x1120
	ds_read_b64 v[234:235], v248 offset:0x1130
	s_waitcnt lgkmcnt(4)
	v_mfma_f32_32x32x16_bf16 v[18:33], v[236:239], v[244:247], v[18:33]
	ds_read_b64 v[236:237], v248 offset:0x2220
	ds_read_b64 v[238:239], v248 offset:0x2230
	v_mfma_f32_32x32x16_bf16 v[2:17], v[240:243], v[244:247], v[2:17]
	v_cvt_pk_bf16_f32 v244, v74, v75
	v_cvt_pk_bf16_f32 v245, v76, v77
	v_cvt_pk_bf16_f32 v246, v78, v79
	v_cvt_pk_bf16_f32 v247, v80, v81
	ds_read_b64 v[240:241], v248 offset:0x3320
	ds_read_b64 v[242:243], v248 offset:0x3330
	s_waitcnt lgkmcnt(4)
	v_mfma_f32_32x32x16_bf16 v[50:65], v[228:231], v[244:247], v[50:65]
	ds_read_b64 v[228:229], v248 offset:64
	ds_read_b64 v[230:231], v248 offset:0x50
	v_mfma_f32_32x32x16_bf16 v[34:49], v[232:235], v[244:247], v[34:49]
	ds_read_b64 v[232:233], v248 offset:0x1140
	ds_read_b64 v[234:235], v248 offset:0x1150
	s_waitcnt lgkmcnt(4)
	v_mfma_f32_32x32x16_bf16 v[18:33], v[236:239], v[244:247], v[18:33]
	ds_read_b64 v[236:237], v248 offset:0x2240
	ds_read_b64 v[238:239], v248 offset:0x2250
	v_mfma_f32_32x32x16_bf16 v[2:17], v[240:243], v[244:247], v[2:17]
	v_cvt_pk_bf16_f32 v244, v82, v83
	v_cvt_pk_bf16_f32 v245, v84, v85
	v_cvt_pk_bf16_f32 v246, v86, v87
	v_cvt_pk_bf16_f32 v247, v88, v89
	ds_read_b64 v[240:241], v248 offset:0x3340
	ds_read_b64 v[242:243], v248 offset:0x3350
	s_waitcnt lgkmcnt(4)
	v_mfma_f32_32x32x16_bf16 v[50:65], v[228:231], v[244:247], v[50:65]
	ds_read_b64 v[228:229], v248 offset:0x60
	ds_read_b64 v[230:231], v248 offset:0x70
	v_mfma_f32_32x32x16_bf16 v[34:49], v[232:235], v[244:247], v[34:49]
	ds_read_b64 v[232:233], v248 offset:0x1160
	ds_read_b64 v[234:235], v248 offset:0x1170
	s_waitcnt lgkmcnt(4)
	v_mfma_f32_32x32x16_bf16 v[18:33], v[236:239], v[244:247], v[18:33]
	ds_read_b64 v[236:237], v248 offset:0x2260
	ds_read_b64 v[238:239], v248 offset:0x2270
	v_mfma_f32_32x32x16_bf16 v[2:17], v[240:243], v[244:247], v[2:17]
	v_cvt_pk_bf16_f32 v244, v90, v91
	v_cvt_pk_bf16_f32 v245, v92, v93
	v_cvt_pk_bf16_f32 v246, v94, v95
	v_cvt_pk_bf16_f32 v247, v96, v97
	ds_read_b64 v[240:241], v248 offset:0x3360
	ds_read_b64 v[242:243], v248 offset:0x3370
	s_waitcnt lgkmcnt(4)
	v_mfma_f32_32x32x16_bf16 v[50:65], v[228:231], v[244:247], v[50:65]
	v_mfma_f32_32x32x16_bf16 v[34:49], v[232:235], v[244:247], v[34:49]
	s_waitcnt lgkmcnt(0)
	v_mfma_f32_32x32x16_bf16 v[18:33], v[236:239], v[244:247], v[18:33]
	v_mfma_f32_32x32x16_bf16 v[2:17], v[240:243], v[244:247], v[2:17]
	s_setprio 0
	s_andn2_b64 vcc, exec, s[10:11]
	s_cbranch_vccnz .LBB0_827
	s_bitcmp1_b32 s18, 0
	s_cselect_b32 s6, 0xa800, 0
	v_add3_u32 v228, s6, v167, v169
	v_add3_u32 v229, s6, v199, v217
	v_add3_u32 v230, s6, v220, v221
	s_waitcnt vmcnt(2)
	ds_write_b128 v228, v[146:149]
	s_waitcnt vmcnt(1)
	ds_write_b128 v229, v[154:157]
	s_waitcnt vmcnt(0)
	ds_write_b128 v230, v[162:165]

; #define SBAR() __builtin_amdgcn_sched_barrier(0)
; template <int DQK, int MODE, bool PIPE>
; DI void attn_core(const u16* __restrict__ Qg, const u16* __restrict__ Kg, const u16* __restrict__ Vtg, int ntiles,
;                   int kr_lo, int rs, int r_q, int c_q, int cs, const float* biasL, char* lds, f32x16 (&o)[4], float& l_out, int tid) {
;     ...
;     for (int i = 0; i < 16; ++i) { p0[i] = __builtin_amdgcn_exp2f(p0[i]); p1[i] = __builtin_amdgcn_exp2f(p1[i]); ps += p0[i] + p1[i]; }
;     l += ps;
;     const char* vb = lds + (t & 1) * A_BUF + A_VOFF + r32 * 136 + h * 8;
;     {
;       bf16x8 pfc;
;       constexpr int R = PV_RING;
;       const unsigned vaddr = (unsigned)(size_t)vb;
;       s16x4 vlo[R], vhi[R];
;       SBAR();
;       vlo[0] = lds_rd64<0>(vaddr); vhi[0] = lds_rd64<16>(vaddr);
;       vlo[1] = lds_rd64<32 * 136>(vaddr); vhi[1] = lds_rd64<32 * 136 + 16>(vaddr);
;       if (R > 2) { vlo[2 % R] = lds_rd64<64 * 136>(vaddr); vhi[2 % R] = lds_rd64<64 * 136 + 16>(vaddr); }
;       if (R > 3) { vlo[3 % R] = lds_rd64<96 * 136>(vaddr); vhi[3 % R] = lds_rd64<96 * 136 + 16>(vaddr); }
;       SBAR();
;       __builtin_amdgcn_s_setprio(1);
;       PvStep<0, 16, R>::run(vaddr, vlo, vhi, p0, p1, pfc, o);
;       __builtin_amdgcn_s_setprio(0);
;     ...
;       if (t + 2 < ntiles) swriteK(t & 1);
;       if (t + 3 < ntiles) gloadK(t + 3);
;     } else {
;       if (is_active(t)) { qk(t, c0, c1); sm_pv(t, c0, c1); }
;       if (t + 1 < ntiles) swriteK((t + 1) & 1);
;       if (t + 2 < ntiles) gloadK(t + 2);
.LBB0_844:
	v_exp_f32_e32 v82, v82
	v_exp_f32_e32 v98, v98
	v_exp_f32_e32 v83, v83
	v_exp_f32_e32 v99, v99
	v_exp_f32_e32 v84, v84
	v_exp_f32_e32 v100, v100
	v_exp_f32_e32 v85, v85
	v_exp_f32_e32 v101, v101
	v_exp_f32_e32 v86, v86
	v_exp_f32_e32 v102, v102
	v_exp_f32_e32 v87, v87
	v_exp_f32_e32 v103, v103
	v_exp_f32_e32 v88, v88
	v_exp_f32_e32 v104, v104
	v_exp_f32_e32 v89, v89
	v_exp_f32_e32 v105, v105
	v_exp_f32_e32 v90, v90
	v_exp_f32_e32 v106, v106
	v_exp_f32_e32 v91, v91
	v_exp_f32_e32 v107, v107
	v_exp_f32_e32 v92, v92
	v_exp_f32_e32 v108, v108
	v_exp_f32_e32 v93, v93
	v_exp_f32_e32 v109, v109
	v_exp_f32_e32 v94, v94
	v_exp_f32_e32 v110, v110
	v_exp_f32_e32 v95, v95
	v_exp_f32_e32 v111, v111
	v_exp_f32_e32 v96, v96
	v_exp_f32_e32 v112, v112
	v_exp_f32_e32 v97, v97
	v_exp_f32_e32 v113, v113
	v_add_u32_e32 v177, s15, v168
	v_add3_u32 v177, v177, v166, s33
	ds_read_b64 v[216:217], v177 offset:0
	ds_read_b64 v[218:219], v177 offset:16
	ds_read_b64 v[220:221], v177 offset:0x1100
	ds_read_b64 v[222:223], v177 offset:0x1110
	ds_read_b64 v[224:225], v177 offset:0x2200
	ds_read_b64 v[226:227], v177 offset:0x2210
	ds_read_b64 v[228:229], v177 offset:0x3300
	ds_read_b64 v[230:231], v177 offset:0x3310
	s_setprio 1
	s_waitcnt lgkmcnt(4)
	v_cvt_pk_bf16_f32 v232, v82, v83
	v_cvt_pk_bf16_f32 v233, v84, v85
	v_cvt_pk_bf16_f32 v234, v86, v87
	v_cvt_pk_bf16_f32 v235, v88, v89
	s_nop 1
	v_mfma_f32_32x32x16_bf16 v[66:81], v[216:219], v[232:235], v[66:81]
	ds_read_b64 v[216:217], v177 offset:32
	ds_read_b64 v[218:219], v177 offset:48
	v_mfma_f32_32x32x16_bf16 v[50:65], v[220:223], v[232:235], v[50:65]
	ds_read_b64 v[220:221], v177 offset:0x1120
	ds_read_b64 v[222:223], v177 offset:0x1130
	s_waitcnt lgkmcnt(4)
	v_mfma_f32_32x32x16_bf16 v[34:49], v[224:227], v[232:235], v[34:49]
	ds_read_b64 v[224:225], v177 offset:0x2220
	ds_read_b64 v[226:227], v177 offset:0x2230
	v_mfma_f32_32x32x16_bf16 v[2:17], v[228:231], v[232:235], v[2:17]
	v_cvt_pk_bf16_f32 v232, v90, v91
	v_cvt_pk_bf16_f32 v233, v92, v93
	v_cvt_pk_bf16_f32 v234, v94, v95
	v_cvt_pk_bf16_f32 v235, v96, v97
	ds_read_b64 v[228:229], v177 offset:0x3320
	ds_read_b64 v[230:231], v177 offset:0x3330
	s_waitcnt lgkmcnt(4)
	v_mfma_f32_32x32x16_bf16 v[66:81], v[216:219], v[232:235], v[66:81]
	ds_read_b64 v[216:217], v177 offset:64
	ds_read_b64 v[218:219], v177 offset:0x50
	v_mfma_f32_32x32x16_bf16 v[50:65], v[220:223], v[232:235], v[50:65]
	ds_read_b64 v[220:221], v177 offset:0x1140
	ds_read_b64 v[222:223], v177 offset:0x1150
	s_waitcnt lgkmcnt(4)
	v_mfma_f32_32x32x16_bf16 v[34:49], v[224:227], v[232:235], v[34:49]
	ds_read_b64 v[224:225], v177 offset:0x2240
	ds_read_b64 v[226:227], v177 offset:0x2250
	v_mfma_f32_32x32x16_bf16 v[2:17], v[228:231], v[232:235], v[2:17]
	v_cvt_pk_bf16_f32 v232, v98, v99
	v_cvt_pk_bf16_f32 v233, v100, v101
	v_cvt_pk_bf16_f32 v234, v102, v103
	v_cvt_pk_bf16_f32 v235, v104, v105
	ds_read_b64 v[228:229], v177 offset:0x3340
	ds_read_b64 v[230:231], v177 offset:0x3350
	s_waitcnt lgkmcnt(4)
	v_mfma_f32_32x32x16_bf16 v[66:81], v[216:219], v[232:235], v[66:81]
	ds_read_b64 v[216:217], v177 offset:0x60
	ds_read_b64 v[218:219], v177 offset:0x70
	v_mfma_f32_32x32x16_bf16 v[50:65], v[220:223], v[232:235], v[50:65]
	ds_read_b64 v[220:221], v177 offset:0x1160
	ds_read_b64 v[222:223], v177 offset:0x1170
	s_waitcnt lgkmcnt(4)
	v_mfma_f32_32x32x16_bf16 v[34:49], v[224:227], v[232:235], v[34:49]
	ds_read_b64 v[224:225], v177 offset:0x2260
	ds_read_b64 v[226:227], v177 offset:0x2270
	v_mfma_f32_32x32x16_bf16 v[2:17], v[228:231], v[232:235], v[2:17]
	v_cvt_pk_bf16_f32 v232, v106, v107
	v_cvt_pk_bf16_f32 v233, v108, v109
	v_cvt_pk_bf16_f32 v234, v110, v111
	v_cvt_pk_bf16_f32 v235, v112, v113
	ds_read_b64 v[228:229], v177 offset:0x3360
	ds_read_b64 v[230:231], v177 offset:0x3370
	s_waitcnt lgkmcnt(4)
	v_mfma_f32_32x32x16_bf16 v[66:81], v[216:219], v[232:235], v[66:81]
	v_mfma_f32_32x32x16_bf16 v[50:65], v[220:223], v[232:235], v[50:65]
	s_waitcnt lgkmcnt(0)
	v_mfma_f32_32x32x16_bf16 v[34:49], v[224:227], v[232:235], v[34:49]
	v_mfma_f32_32x32x16_bf16 v[2:17], v[228:231], v[232:235], v[2:17]
	s_setprio 0
	s_andn2_b64 vcc, exec, s[0:1]
	s_cbranch_vccnz .LBB0_846
	s_bitcmp1_b32 s14, 0
	s_cselect_b32 s0, 0xa800, 0
	v_add_u32_e32 v177, s0, v143
	s_waitcnt vmcnt(0)
	ds_write_b128 v177, v[138:141]

; #define MFMA(a, b, c) __builtin_amdgcn_mfma_f32_32x32x16_bf16((a), (b), (c), 0, 0, 0)
; template <int N> DI void lgkm_wait() { asm volatile("s_waitcnt lgkmcnt(%0)" :: "i"(N) : "memory"); }
; #define SBAR() __builtin_amdgcn_sched_barrier(0)
;   static DI void run(unsigned vaddr, s16x4 (&lo)[R], s16x4 (&hi)[R], const f32x16& p0, const f32x16& p1, bf16x8& pfc, f32x16 (&o)[4]) {
;     constexpr int issued = (J + R < NF) ? (J + R) : NF;
;     if constexpr ((J & 3) == 0) {
;       if constexpr ((J >> 2) == 0) pfc = pack8<0>(p0);
;       else if constexpr ((J >> 2) == 1) pfc = pack8<8>(p0);
;       else if constexpr ((J >> 2) == 2) pfc = pack8<0>(p1);
;       else pfc = pack8<8>(p1);
;     }
;     lgkm_wait<2 * (issued - J - 1)>(); SBAR();
;     o[J & 3] = MFMA(__builtin_shufflevector(lo[J % R], hi[J % R], 0, 1, 2, 3, 4, 5, 6, 7), pfc, o[J & 3]);
;     SBAR();
;     if (J + R < NF) {
;       constexpr int off = ((J + R) & 3) * 32 * 136 + ((J + R) >> 2) * 32;
;       lo[J % R] = lds_rd64<off>(vaddr); hi[J % R] = lds_rd64<off + 16>(vaddr); SBAR();
;     }
;     if constexpr (J + 1 < NF) PvStep<J + 1, NF, R>::run(vaddr, lo, hi, p0, p1, pfc, o);
; template <int DQK, int MODE, bool PIPE>
; DI void attn_core(const u16* __restrict__ Qg, const u16* __restrict__ Kg, const u16* __restrict__ Vtg, int ntiles,
;                   int kr_lo, int rs, int r_q, int c_q, int cs, const float* biasL, char* lds, f32x16 (&o)[4], float& l_out, int tid) {
;     ...
;     for (int i = 0; i < 16; ++i) { p0[i] = __builtin_amdgcn_exp2f(p0[i]); p1[i] = __builtin_amdgcn_exp2f(p1[i]); ps += p0[i] + p1[i]; }
;     l += ps;
;     const char* vb = lds + (t & 1) * A_BUF + A_VOFF + r32 * 136 + h * 8;
;     {
;       bf16x8 pfc;
;       constexpr int R = PV_RING;
;       const unsigned vaddr = (unsigned)(size_t)vb;
;       s16x4 vlo[R], vhi[R];
;       SBAR();
;       vlo[0] = lds_rd64<0>(vaddr); vhi[0] = lds_rd64<16>(vaddr);
;       vlo[1] = lds_rd64<32 * 136>(vaddr); vhi[1] = lds_rd64<32 * 136 + 16>(vaddr);
;       if (R > 2) { vlo[2 % R] = lds_rd64<64 * 136>(vaddr); vhi[2 % R] = lds_rd64<64 * 136 + 16>(vaddr); }
;       if (R > 3) { vlo[3 % R] = lds_rd64<96 * 136>(vaddr); vhi[3 % R] = lds_rd64<96 * 136 + 16>(vaddr); }
;       SBAR();
;       __builtin_amdgcn_s_setprio(1);
;       PvStep<0, 16, R>::run(vaddr, vlo, vhi, p0, p1, pfc, o);
;       __builtin_amdgcn_s_setprio(0);
.LBB0_860:
	v_exp_f32_e32 v82, v82
	v_exp_f32_e32 v98, v98
	v_exp_f32_e32 v83, v83
	v_exp_f32_e32 v99, v99
	v_exp_f32_e32 v84, v84
	v_exp_f32_e32 v100, v100
	v_exp_f32_e32 v85, v85
	v_exp_f32_e32 v101, v101
	v_exp_f32_e32 v86, v86
	v_exp_f32_e32 v102, v102
	v_exp_f32_e32 v87, v87
	v_exp_f32_e32 v103, v103
	v_exp_f32_e32 v88, v88
	v_exp_f32_e32 v104, v104
	v_exp_f32_e32 v89, v89
	v_exp_f32_e32 v105, v105
	v_exp_f32_e32 v90, v90
	v_exp_f32_e32 v106, v106
	v_exp_f32_e32 v91, v91
	v_exp_f32_e32 v107, v107
	v_exp_f32_e32 v92, v92
	v_exp_f32_e32 v108, v108
	v_exp_f32_e32 v93, v93
	v_exp_f32_e32 v109, v109
	v_exp_f32_e32 v94, v94
	v_exp_f32_e32 v110, v110
	v_exp_f32_e32 v95, v95
	v_exp_f32_e32 v111, v111
	v_exp_f32_e32 v96, v96
	v_exp_f32_e32 v112, v112
	v_exp_f32_e32 v97, v97
	v_exp_f32_e32 v113, v113
	v_add_u32_e32 v156, s12, v168
	v_add3_u32 v160, v156, v166, s33
	ds_read_b64 v[156:157], v160 offset:0
	ds_read_b64 v[158:159], v160 offset:16
	ds_read_b64 v[170:171], v160 offset:0x1100
	ds_read_b64 v[172:173], v160 offset:0x1110
	ds_read_b64 v[174:175], v160 offset:0x2200
	ds_read_b64 v[176:177], v160 offset:0x2210
	ds_read_b64 v[216:217], v160 offset:0x3300
	ds_read_b64 v[218:219], v160 offset:0x3310
	s_setprio 1
	s_waitcnt lgkmcnt(4)
	v_cvt_pk_bf16_f32 v220, v82, v83
	v_cvt_pk_bf16_f32 v221, v84, v85
	v_cvt_pk_bf16_f32 v222, v86, v87
	v_cvt_pk_bf16_f32 v223, v88, v89
	s_nop 1
	v_mfma_f32_32x32x16_bf16 v[66:81], v[156:159], v[220:223], v[66:81]
	ds_read_b64 v[156:157], v160 offset:32
	ds_read_b64 v[158:159], v160 offset:48
	v_mfma_f32_32x32x16_bf16 v[50:65], v[170:173], v[220:223], v[50:65]
	ds_read_b64 v[170:171], v160 offset:0x1120
	ds_read_b64 v[172:173], v160 offset:0x1130
	s_waitcnt lgkmcnt(4)
	v_mfma_f32_32x32x16_bf16 v[18:33], v[174:177], v[220:223], v[18:33]
	ds_read_b64 v[174:175], v160 offset:0x2220
	ds_read_b64 v[176:177], v160 offset:0x2230
	v_mfma_f32_32x32x16_bf16 v[2:17], v[216:219], v[220:223], v[2:17]
	v_cvt_pk_bf16_f32 v220, v90, v91
	v_cvt_pk_bf16_f32 v221, v92, v93
	v_cvt_pk_bf16_f32 v222, v94, v95
	v_cvt_pk_bf16_f32 v223, v96, v97
	ds_read_b64 v[216:217], v160 offset:0x3320
	ds_read_b64 v[218:219], v160 offset:0x3330
	s_waitcnt lgkmcnt(4)
	v_mfma_f32_32x32x16_bf16 v[66:81], v[156:159], v[220:223], v[66:81]
	ds_read_b64 v[156:157], v160 offset:64
	ds_read_b64 v[158:159], v160 offset:0x50
	v_mfma_f32_32x32x16_bf16 v[50:65], v[170:173], v[220:223], v[50:65]
	ds_read_b64 v[170:171], v160 offset:0x1140
	ds_read_b64 v[172:173], v160 offset:0x1150
	s_waitcnt lgkmcnt(4)
	v_mfma_f32_32x32x16_bf16 v[18:33], v[174:177], v[220:223], v[18:33]
	ds_read_b64 v[174:175], v160 offset:0x2240
	ds_read_b64 v[176:177], v160 offset:0x2250
	v_mfma_f32_32x32x16_bf16 v[2:17], v[216:219], v[220:223], v[2:17]
	v_cvt_pk_bf16_f32 v220, v98, v99
	v_cvt_pk_bf16_f32 v221, v100, v101
	v_cvt_pk_bf16_f32 v222, v102, v103
	v_cvt_pk_bf16_f32 v223, v104, v105
	ds_read_b64 v[216:217], v160 offset:0x3340
	ds_read_b64 v[218:219], v160 offset:0x3350
	s_waitcnt lgkmcnt(4)
	v_mfma_f32_32x32x16_bf16 v[66:81], v[156:159], v[220:223], v[66:81]
	ds_read_b64 v[156:157], v160 offset:0x60
	ds_read_b64 v[158:159], v160 offset:0x70
	v_mfma_f32_32x32x16_bf16 v[50:65], v[170:173], v[220:223], v[50:65]
	ds_read_b64 v[170:171], v160 offset:0x1160
	ds_read_b64 v[172:173], v160 offset:0x1170
	s_waitcnt lgkmcnt(4)
	v_mfma_f32_32x32x16_bf16 v[18:33], v[174:177], v[220:223], v[18:33]
	ds_read_b64 v[174:175], v160 offset:0x2260
	ds_read_b64 v[176:177], v160 offset:0x2270
	v_mfma_f32_32x32x16_bf16 v[2:17], v[216:219], v[220:223], v[2:17]
	v_cvt_pk_bf16_f32 v220, v106, v107
	v_cvt_pk_bf16_f32 v221, v108, v109
	v_cvt_pk_bf16_f32 v222, v110, v111
	v_cvt_pk_bf16_f32 v223, v112, v113
	ds_read_b64 v[216:217], v160 offset:0x3360
	ds_read_b64 v[218:219], v160 offset:0x3370
	s_waitcnt lgkmcnt(4)
	v_mfma_f32_32x32x16_bf16 v[66:81], v[156:159], v[220:223], v[66:81]
	v_mfma_f32_32x32x16_bf16 v[50:65], v[170:173], v[220:223], v[50:65]
	s_waitcnt lgkmcnt(0)
	v_mfma_f32_32x32x16_bf16 v[18:33], v[174:177], v[220:223], v[18:33]
	v_mfma_f32_32x32x16_bf16 v[2:17], v[216:219], v[220:223], v[2:17]
	s_setprio 0
	s_andn2_b64 vcc, exec, s[0:1]
	s_cbranch_vccnz .LBB0_862
	s_bitcmp1_b32 s11, 0
	s_cselect_b32 s0, 0xa800, 0
	v_add_u32_e32 v156, s0, v143
	s_waitcnt vmcnt(0)
	ds_write_b128 v156, v[138:141]
